# S5 tables item moved from before this workgroup's in-projection units to after them (just before the first barrier of the layer)
# baseline (speedup 1.0000x reference)
.LBB0_73:
	v_readlane_b32 s2, v251, 28
	s_mov_b32 s4, s12
	s_mov_b32 s5, s77
	v_readlane_b32 s3, v251, 29
	s_lshl_b64 s[6:7], s[4:5], 15
	s_andn2_b64 vcc, exec, s[2:3]
	v_writelane_b32 v250, s4, 21
	s_mul_i32 s62, s4, 0x208000
	s_nop 0
	v_writelane_b32 v250, s5, 22
	s_branch .LBB0_102

.LBB0_655:
	s_waitcnt vmcnt(0)
	s_waitcnt vmcnt(0) lgkmcnt(0)
	s_barrier
	v_readlane_b32 s2, v251, 28
	v_readlane_b32 s3, v251, 29
	v_readlane_b32 s4, v250, 21
	v_readlane_b32 s5, v250, 22
	s_andn2_b64 vcc, exec, s[2:3]
	s_cbranch_vccnz .Ltab_skip
	s_lshl_b64 s[6:7], s[4:5], 15
	s_mul_i32 s62, s4, 0x208000
	v_readlane_b32 s4, v250, 21
	s_lshl_b32 s20, s4, 6
	v_readlane_b32 s2, v251, 30
	v_readlane_b32 s5, v250, 22
	s_add_u32 s21, s2, s62
	v_readlane_b32 s2, v251, 31
	s_addc_u32 s28, s2, 0
	s_lshl_b64 s[2:3], s[4:5], 24
	v_readlane_b32 s4, v251, 32
	s_add_u32 s29, s4, s2
	v_readlane_b32 s4, v251, 33
	s_addc_u32 s36, s4, s3
	v_readlane_b32 s4, v251, 34
	s_add_u32 s37, s4, s2
	v_readlane_b32 s2, v251, 35
	s_addc_u32 s38, s2, s3
	v_readlane_b32 s2, v251, 36
	s_add_u32 s39, s2, s6
	v_readlane_b32 s2, v251, 37
	s_addc_u32 s40, s2, s7
	v_readlane_b32 s2, v252, 61
	s_add_i32 s4, s2, s20
	s_mov_b32 s8, s2

.Ltab_skip:
	s_mov_b64 s[0:1], exec
	v_readlane_b32 s2, v251, 8
	v_readlane_b32 s3, v251, 9
	s_and_b64 s[2:3], s[0:1], s[2:3]
	s_mov_b64 exec, s[2:3]
	s_cbranch_execz .LBB0_707
	v_readlane_b32 s2, v254, 26
	s_waitcnt vmcnt(0) expcnt(0) lgkmcnt(0)
	s_nop 0
	v_mov_b32_e32 v0, s2
	ds_read_b32 v3, v0
	v_readlane_b32 s2, v254, 27
	s_waitcnt lgkmcnt(0)
	v_cmp_ne_u32_e32 vcc, 0, v3
	v_mov_b32_e32 v0, s2
	ds_read_b32 v2, v0
	s_cbranch_vccnz .LBB0_671
	s_mov_b32 s10, 1
	s_branch .LBB0_659
